# v29 + rw_outprep row loop de-serialised: all 32 loads of a row issued up front (registers renamed, fmac -> fma with explicit old value), one wait, then the original math and stores
# baseline (speedup 1.0000x reference)
.LBB0_829:
	v_add_co_u32_e32 v72, vcc, 0x4200000, v44
	s_mov_b32 s0, 0xf5b00000
	v_addc_co_u32_e32 v73, vcc, 0, v45, vcc
	v_add_co_u32_e32 v74, vcc, 0x6300000, v44
	global_load_dwordx4 v[76:79], v[72:73], off
	v_addc_co_u32_e32 v75, vcc, 0, v45, vcc
	v_add_co_u32_e32 v80, vcc, 0xf3a00000, v44
	global_load_dwordx4 v[82:85], v[74:75], off
	v_addc_co_u32_e32 v81, vcc, -1, v45, vcc
	v_add_co_u32_e32 v86, vcc, s0, v44
	global_load_dwordx4 v[88:91], v[80:81], off
	v_addc_co_u32_e32 v87, vcc, -1, v45, vcc
	global_load_dwordx4 v[96:99], v[86:87], off
	global_load_dwordx4 v[100:103], v[44:45], off
	v_add_co_u32_e32 v80, vcc, s6, v44
	s_mov_b32 s0, 0xf3a01000
	v_addc_co_u32_e32 v81, vcc, 0, v45, vcc
	global_load_dwordx4 v[120:123], v[80:81], off
	global_load_dwordx4 v[124:127], v[36:37], off offset:16
	global_load_dwordx4 v[128:131], v[36:37], off
	global_load_dwordx4 v[132:135], v[36:37], off offset:48
	global_load_dwordx4 v[136:139], v[36:37], off offset:32
	global_load_dwordx4 v[140:143], v[38:39], off offset:16
	global_load_dwordx4 v[144:147], v[38:39], off
	global_load_dwordx4 v[148:151], v[38:39], off offset:48
	global_load_dwordx4 v[152:155], v[38:39], off offset:32
	v_add_u32_e32 v71, s50, v71
	v_add_co_u32_e32 v86, vcc, s0, v44
	s_mov_b32 s0, 0xf5b01000
	v_addc_co_u32_e32 v87, vcc, -1, v45, vcc
	v_add_co_u32_e32 v92, vcc, s0, v44
	v_addc_co_u32_e32 v93, vcc, -1, v45, vcc
	global_load_dwordx4 v[156:159], v[72:73], off offset:16
	global_load_dwordx4 v[160:163], v[74:75], off offset:16
	s_mov_b32 s0, 0xf7c00000
	global_load_dwordx4 v[72:75], v[86:87], off offset:-4080
	global_load_dwordx4 v[164:167], v[92:93], off offset:-4080
	global_load_dwordx4 v[168:171], v[44:45], off offset:16
	global_load_dwordx4 v[172:175], v[80:81], off offset:16
	v_add_co_u32_e32 v80, vcc, s0, v44
	s_mov_b32 s0, 0xf9d00000
	v_addc_co_u32_e32 v81, vcc, -1, v45, vcc
	global_load_dwordx4 v[176:179], v[80:81], off
	v_add_co_u32_e32 v80, vcc, s0, v44
	v_addc_co_u32_e32 v81, vcc, -1, v45, vcc
	global_load_dwordx4 v[184:187], v[80:81], off
	s_mov_b32 s0, 0xf7c01000
	global_load_dwordx4 v[188:191], v[40:41], off offset:16
	global_load_dwordx4 v[192:195], v[40:41], off
	global_load_dwordx4 v[196:199], v[42:43], off offset:16
	global_load_dwordx4 v[200:203], v[42:43], off
	v_mov_b32_e32 v81, v69
	v_add_co_u32_e32 v86, vcc, s0, v44
	s_mov_b32 s0, 0xf9d01000
	v_addc_co_u32_e32 v87, vcc, -1, v45, vcc
	v_add_co_u32_e32 v92, vcc, s0, v44
	global_load_dwordx4 v[204:207], v[86:87], off offset:-4080
	v_addc_co_u32_e32 v93, vcc, -1, v45, vcc
	global_load_dwordx4 v[208:211], v[92:93], off offset:-4080
	v_add_co_u32_e32 v86, vcc, s10, v44
	v_addc_co_u32_e32 v87, vcc, 0, v45, vcc
	s_waitcnt vmcnt(0)
	v_lshlrev_b32_e32 v92, 16, v120
	s_nop 0
	v_add_f32_e32 v93, -1.0, v92
	v_lshlrev_b32_e32 v92, 16, v100
	s_nop 0
	v_add_f32_e32 v212, -1.0, v92
	v_and_b32_e32 v92, 0xffff0000, v120
	v_lshlrev_b32_e32 v213, 16, v96
	v_fma_f32 v214, v128, v212, 1.0
	v_fma_f32 v212, v128, v93, 1.0
	v_and_b32_e32 v93, 0xffff0000, v100
	v_add_f32_e32 v215, -1.0, v92
	v_mul_f32_e32 v92, v212, v213
	v_and_b32_e32 v212, 0xffff0000, v96
	v_add_f32_e32 v216, -1.0, v93
	v_fma_f32 v93, v129, v215, 1.0
	v_lshlrev_b32_e32 v215, 16, v88
	v_fma_f32 v217, v214, v213, v92
	v_fma_f32 v92, v129, v216, 1.0
	v_mul_f32_e32 v213, v93, v212
	v_mul_f32_e32 v93, v217, v215
	v_and_b32_e32 v214, 0xffff0000, v88
	v_fma_f32 v215, v92, v212, v213
	v_lshlrev_b32_e32 v92, 16, v121
	v_fma_f32 v212, v144, v93, 0
	v_mul_f32_e32 v93, v215, v214
	v_lshlrev_b32_e32 v213, 16, v101
	v_add_f32_e32 v214, -1.0, v92
	v_fma_f32 v92, v145, v93, v212
	v_lshlrev_b32_e32 v93, 16, v97
	v_add_f32_e32 v212, -1.0, v213
	v_fma_f32 v213, v130, v214, 1.0
	v_fma_f32 v214, v130, v212, 1.0
	v_mul_f32_e32 v212, v213, v93
	v_lshlrev_b32_e32 v213, 16, v89
	v_fma_f32 v215, v214, v93, v212
	s_nop 0
	v_mul_f32_e32 v93, v215, v213
	s_nop 0
	v_fma_f32 v212, v93, v146, v92
	v_and_b32_e32 v92, 0xffff0000, v97
	v_and_b32_e32 v93, 0xffff0000, v121
	v_and_b32_e32 v213, 0xffff0000, v101
	v_add_f32_e32 v214, -1.0, v93
	v_add_f32_e32 v93, -1.0, v213
	v_fma_f32 v213, v131, v214, 1.0
	v_fma_f32 v214, v131, v93, 1.0
	v_mul_f32_e32 v93, v213, v92
	v_and_b32_e32 v128, 0xffff0000, v89
	v_fma_f32 v129, v214, v92, v93
	v_lshlrev_b32_e32 v92, 16, v122
	v_mul_f32_e32 v93, v129, v128
	v_lshlrev_b32_e32 v128, 16, v102
	v_add_f32_e32 v129, -1.0, v92
	v_fma_f32 v92, v93, v147, v212
	v_lshlrev_b32_e32 v93, 16, v98
	v_add_f32_e32 v130, -1.0, v128
	v_fma_f32 v128, v124, v129, 1.0
	v_fma_f32 v129, v130, v124, 1.0
	v_mul_f32_e32 v130, v128, v93
	v_lshlrev_b32_e32 v128, 16, v90
	v_fma_f32 v131, v129, v93, v130
	s_nop 0
	v_mul_f32_e32 v93, v131, v128
	v_and_b32_e32 v128, 0xffff0000, v122
	v_and_b32_e32 v129, 0xffff0000, v102
	v_add_f32_e32 v130, -1.0, v128
	v_fma_f32 v128, v93, v140, v92
	v_and_b32_e32 v92, 0xffff0000, v98
	v_add_f32_e32 v93, -1.0, v129
	v_fma_f32 v129, v130, v125, 1.0
	v_fma_f32 v130, v93, v125, 1.0
	v_mul_f32_e32 v93, v129, v92
	v_and_b32_e32 v129, 0xffff0000, v90
	v_fma_f32 v131, v130, v92, v93
	s_nop 0
	v_mul_f32_e32 v92, v131, v129
	s_nop 0
	v_fma_f32 v93, v92, v141, v128
	v_and_b32_e32 v129, 0xffff0000, v99
	v_lshlrev_b32_e32 v128, 16, v99
	v_and_b32_e32 v97, 0xffff0000, v123
	v_lshlrev_b32_e32 v96, 16, v123
	v_and_b32_e32 v99, 0xffff0000, v103
	v_lshlrev_b32_e32 v98, 16, v103
	v_pk_add_f32 v[100:101], v[96:97], -1.0 op_sel_hi:[1,0]
	v_pk_add_f32 v[96:97], v[98:99], -1.0 op_sel_hi:[1,0]
	v_pk_fma_f32 v[98:99], v[100:101], v[126:127], 1.0 op_sel_hi:[1,1,0]
	v_pk_fma_f32 v[100:101], v[96:97], v[126:127], 1.0 op_sel_hi:[1,1,0]
	v_pk_mul_f32 v[96:97], v[98:99], v[128:129]
	v_and_b32_e32 v99, 0xffff0000, v91
	v_lshlrev_b32_e32 v98, 16, v91
	v_pk_fma_f32 v[88:89], v[100:101], v[128:129], v[96:97]
	s_nop 0
	v_pk_mul_f32 v[90:91], v[88:89], v[98:99]
	s_nop 0
	v_pk_mul_f32 v[88:89], v[90:91], v[142:143]
	s_nop 0
	v_add_f32_e32 v90, v88, v93
	s_nop 0
	v_add_f32_e32 v91, v89, v90
	v_and_b32_e32 v89, 0xffff0000, v156
	v_lshlrev_b32_e32 v88, 16, v156
	v_and_b32_e32 v93, 0xffff0000, v160
	v_and_b32_e32 v97, 0xffff0000, v168
	v_lshlrev_b32_e32 v96, 16, v168
	v_and_b32_e32 v99, 0xffff0000, v172
	v_lshlrev_b32_e32 v98, 16, v172
	v_lshlrev_b32_e32 v92, 16, v160
	v_pk_add_f32 v[100:101], v[96:97], -1.0 op_sel_hi:[1,0]
	v_pk_add_f32 v[96:97], v[98:99], -1.0 op_sel_hi:[1,0]
	v_pk_add_f32 v[98:99], v[88:89], v[92:93]
	v_and_b32_e32 v89, 0xffff0000, v164
	v_lshlrev_b32_e32 v88, 16, v164
	v_pk_fma_f32 v[92:93], v[136:137], v[100:101], 1.0 op_sel_hi:[1,1,0]
	v_pk_fma_f32 v[100:101], v[136:137], v[96:97], 1.0 op_sel_hi:[1,1,0]
	v_and_b32_e32 v97, 0xffff0000, v72
	v_pk_mul_f32 v[102:103], v[100:101], v[88:89]
	v_lshlrev_b32_e32 v96, 16, v72
	v_pk_fma_f32 v[100:101], v[92:93], v[88:89], v[102:103]
	v_lshlrev_b32_e32 v88, 16, v161
	v_pk_mul_f32 v[92:93], v[100:101], v[96:97]
	s_nop 0
	v_pk_mul_f32 v[96:97], v[152:153], v[92:93]
	v_and_b32_e32 v93, 0xffff0000, v173
	v_add_f32_e32 v90, v91, v96
	s_nop 0
	v_add_f32_e32 v91, v97, v90
	v_and_b32_e32 v97, 0xffff0000, v157
	v_lshlrev_b32_e32 v96, 16, v157
	v_and_b32_e32 v89, 0xffff0000, v161
	s_nop 0
	v_pk_add_f32 v[100:101], v[96:97], v[88:89]
	v_and_b32_e32 v89, 0xffff0000, v169
	v_lshlrev_b32_e32 v88, 16, v169
	v_lshlrev_b32_e32 v92, 16, v173
	v_pk_add_f32 v[96:97], v[88:89], -1.0 op_sel_hi:[1,0]
	v_pk_add_f32 v[88:89], v[92:93], -1.0 op_sel_hi:[1,0]
	v_and_b32_e32 v93, 0xffff0000, v165
	v_lshlrev_b32_e32 v92, 16, v165
	v_pk_fma_f32 v[102:103], v[138:139], v[96:97], 1.0 op_sel_hi:[1,1,0]
	v_pk_fma_f32 v[96:97], v[138:139], v[88:89], 1.0 op_sel_hi:[1,1,0]
	v_and_b32_e32 v89, 0xffff0000, v73
	v_pk_mul_f32 v[120:121], v[96:97], v[92:93]
	v_lshlrev_b32_e32 v88, 16, v73
	v_pk_fma_f32 v[96:97], v[102:103], v[92:93], v[120:121]
	v_and_b32_e32 v93, 0xffff0000, v170
	v_pk_mul_f32 v[102:103], v[96:97], v[88:89]
	v_lshlrev_b32_e32 v92, 16, v170
	v_pk_mul_f32 v[88:89], v[102:103], v[154:155]
	v_and_b32_e32 v97, 0xffff0000, v174
	v_lshlrev_b32_e32 v96, 16, v174
	v_add_f32_e32 v90, v88, v91
	v_pk_add_f32 v[102:103], v[92:93], -1.0 op_sel_hi:[1,0]
	v_pk_add_f32 v[92:93], v[96:97], -1.0 op_sel_hi:[1,0]
	v_add_f32_e32 v91, v89, v90
	v_and_b32_e32 v89, 0xffff0000, v166
	v_lshlrev_b32_e32 v88, 16, v166
	v_pk_fma_f32 v[96:97], v[102:103], v[132:133], 1.0 op_sel_hi:[1,1,0]
	v_pk_fma_f32 v[102:103], v[92:93], v[132:133], 1.0 op_sel_hi:[1,1,0]
	v_and_b32_e32 v93, 0xffff0000, v74
	v_pk_mul_f32 v[120:121], v[102:103], v[88:89]
	v_lshlrev_b32_e32 v92, 16, v74
	v_pk_fma_f32 v[102:103], v[96:97], v[88:89], v[120:121]
	v_and_b32_e32 v89, 0xffff0000, v171
	v_pk_mul_f32 v[96:97], v[102:103], v[92:93]
	v_lshlrev_b32_e32 v88, 16, v171
	v_pk_mul_f32 v[92:93], v[96:97], v[148:149]
	v_and_b32_e32 v97, 0xffff0000, v175
	v_lshlrev_b32_e32 v96, 16, v175
	v_add_f32_e32 v90, v92, v91
	v_pk_add_f32 v[102:103], v[88:89], -1.0 op_sel_hi:[1,0]
	v_pk_add_f32 v[88:89], v[96:97], -1.0 op_sel_hi:[1,0]
	v_add_f32_e32 v91, v93, v90
	v_and_b32_e32 v93, 0xffff0000, v167
	v_lshlrev_b32_e32 v92, 16, v167
	v_pk_fma_f32 v[96:97], v[102:103], v[134:135], 1.0 op_sel_hi:[1,1,0]
	v_pk_fma_f32 v[102:103], v[88:89], v[134:135], 1.0 op_sel_hi:[1,1,0]
	v_and_b32_e32 v89, 0xffff0000, v75
	v_pk_mul_f32 v[120:121], v[102:103], v[92:93]
	v_lshlrev_b32_e32 v88, 16, v75
	v_pk_fma_f32 v[72:73], v[96:97], v[92:93], v[120:121]
	v_and_b32_e32 v75, 0xffff0000, v82
	v_and_b32_e32 v93, 0xffff0000, v76
	v_lshlrev_b32_e32 v92, 16, v76
	v_lshlrev_b32_e32 v74, 16, v82
	s_nop 0
	v_pk_add_f32 v[96:97], v[92:93], v[74:75]
	v_pk_mul_f32 v[74:75], v[72:73], v[88:89]
	v_add_f32_e32 v72, 0, v96
	s_nop 0
	v_add_f32_e32 v73, v97, v72
	v_pk_mul_f32 v[88:89], v[74:75], v[150:151]
	s_nop 0
	v_add_f32_e32 v72, v88, v91
	s_nop 0
	v_add_f32_e32 v74, v89, v72
	ds_bpermute_b32 v72, v94, v74
	s_waitcnt lgkmcnt(0)
	v_add_f32_e32 v75, v74, v72
	ds_bpermute_b32 v72, v95, v75
	s_waitcnt lgkmcnt(0)
	v_add_f32_e32 v88, v75, v72
	v_and_b32_e32 v75, 0xffff0000, v176
	v_lshlrev_b32_e32 v74, 16, v176
	v_and_b32_e32 v91, 0xffff0000, v178
	v_lshlrev_b32_e32 v90, 16, v178
	v_and_b32_e32 v93, 0xffff0000, v179
	v_lshlrev_b32_e32 v92, 16, v179
	v_lshlrev_b32_e32 v102, 16, v184
	s_nop 0
	v_mul_f32_e32 v72, 0xbfb8aa3b, v102
	s_nop 0
	v_exp_f32_e32 v120, v72
	v_and_b32_e32 v103, 0xffff0000, v184
	v_add_f32_e32 v72, 1.0, v120
	s_nop 0
	v_rcp_f32_e32 v120, v72
	v_mul_f32_e32 v72, 0xbfb8aa3b, v103
	s_nop 0
	v_exp_f32_e32 v122, v72
	s_nop 0
	v_add_f32_e32 v72, 1.0, v122
	s_nop 0
	v_rcp_f32_e32 v121, v72
	v_lshlrev_b32_e32 v122, 16, v83
	v_pk_mul_f32 v[124:125], v[120:121], v[102:103]
	v_and_b32_e32 v103, 0xffff0000, v77
	v_lshlrev_b32_e32 v102, 16, v77
	v_and_b32_e32 v123, 0xffff0000, v83
	s_nop 0
	v_pk_add_f32 v[120:121], v[102:103], v[122:123]
	v_and_b32_e32 v103, 0xffff0000, v185
	v_add_f32_e32 v102, v120, v73
	s_nop 0
	v_add_f32_e32 v89, v121, v102
	v_mov_b32_e32 v73, v103
	v_lshlrev_b32_e32 v72, 16, v185
	s_nop 0
	v_mul_f32_e32 v102, 0xbfb8aa3b, v72
	v_and_b32_e32 v123, 0xffff0000, v177
	v_lshlrev_b32_e32 v122, 16, v177
	v_mul_f32_e32 v103, 0xbfb8aa3b, v73
	v_exp_f32_e32 v126, v102
	v_exp_f32_e32 v102, v103
	v_add_f32_e32 v103, 1.0, v126
	v_add_f32_e32 v126, 1.0, v102
	v_rcp_f32_e32 v128, v103
	v_rcp_f32_e32 v129, v126
	s_nop 0
	v_pk_mul_f32 v[102:103], v[128:129], v[72:73]
	v_and_b32_e32 v73, 0xffff0000, v78
	v_lshlrev_b32_e32 v72, 16, v78
	v_and_b32_e32 v127, 0xffff0000, v84
	v_lshlrev_b32_e32 v126, 16, v84
	s_nop 0
	v_pk_add_f32 v[128:129], v[72:73], v[126:127]
	v_lshlrev_b32_e32 v72, 16, v186
	v_add_f32_e32 v126, v128, v89
	s_nop 0
	v_add_f32_e32 v127, v129, v126
	v_mul_f32_e32 v126, 0xbfb8aa3b, v72
	s_nop 0
	v_exp_f32_e32 v130, v126
	v_and_b32_e32 v73, 0xffff0000, v186
	v_add_f32_e32 v126, 1.0, v130
	s_nop 0
	v_rcp_f32_e32 v130, v126
	v_mul_f32_e32 v126, 0xbfb8aa3b, v73
	s_nop 0
	v_exp_f32_e32 v132, v126
	s_nop 0
	v_add_f32_e32 v126, 1.0, v132
	s_nop 0
	v_rcp_f32_e32 v131, v126
	v_lshlrev_b32_e32 v132, 16, v85
	v_pk_mul_f32 v[134:135], v[130:131], v[72:73]
	v_and_b32_e32 v73, 0xffff0000, v79
	v_lshlrev_b32_e32 v72, 16, v79
	v_and_b32_e32 v133, 0xffff0000, v85
	s_nop 0
	v_pk_add_f32 v[76:77], v[72:73], v[132:133]
	v_and_b32_e32 v73, 0xffff0000, v159
	v_add_f32_e32 v72, v76, v127
	s_nop 0
	v_add_f32_e32 v78, v77, v72
	s_nop 0
	v_add_f32_e32 v79, v78, v98
	s_nop 0
	v_add_f32_e32 v78, v99, v79
	s_nop 0
	v_add_f32_e32 v79, v100, v78
	v_mov_b32_e32 v82, v88
	v_add_f32_e32 v83, v101, v79
	v_mov_b32_e32 v79, v73
	v_lshlrev_b32_e32 v78, 16, v159
	v_and_b32_e32 v73, 0xffff0000, v163
	v_lshlrev_b32_e32 v72, 16, v163
	v_and_b32_e32 v85, 0xffff0000, v158
	v_lshlrev_b32_e32 v84, 16, v158
	v_and_b32_e32 v89, 0xffff0000, v162
	v_lshlrev_b32_e32 v88, 16, v162
	s_nop 0
	v_pk_add_f32 v[126:127], v[84:85], v[88:89]
	v_pk_add_f32 v[84:85], v[78:79], v[72:73]
	v_add_f32_e32 v72, v126, v83
	s_nop 0
	v_add_f32_e32 v73, v127, v72
	s_nop 0
	v_add_f32_e32 v72, v84, v73
	s_nop 0
	v_add_f32_e32 v73, v85, v72
	ds_bpermute_b32 v72, v94, v73
	s_waitcnt lgkmcnt(0)
	v_add_f32_e32 v78, v73, v72
	ds_bpermute_b32 v72, v95, v78
	s_waitcnt lgkmcnt(0)
	v_add_f32_e32 v73, v78, v72
	s_nop 0
	v_mul_f32_e32 v80, 0x3c800000, v73
	s_nop 0
	v_pk_add_f32 v[72:73], v[120:121], v[80:81] op_sel_hi:[1,0] neg_lo:[0,1] neg_hi:[0,1]
	v_and_b32_e32 v79, 0xffff0000, v187
	v_lshlrev_b32_e32 v78, 16, v187
	v_pk_add_f32 v[88:89], v[96:97], v[80:81] op_sel_hi:[1,0] neg_lo:[0,1] neg_hi:[0,1]
	v_pk_add_f32 v[96:97], v[76:77], v[80:81] op_sel_hi:[1,0] neg_lo:[0,1] neg_hi:[0,1]
	v_mul_f32_e32 v76, 0xbfb8aa3b, v78
	v_mul_f32_e32 v77, 0xbfb8aa3b, v79
	v_exp_f32_e32 v120, v76
	v_exp_f32_e32 v76, v77
	v_pk_add_f32 v[130:131], v[128:129], v[80:81] op_sel_hi:[1,0] neg_lo:[0,1] neg_hi:[0,1]
	v_pk_add_f32 v[128:129], v[126:127], v[80:81] op_sel_hi:[1,0] neg_lo:[0,1] neg_hi:[0,1]
	v_add_f32_e32 v77, 1.0, v120
	v_add_f32_e32 v120, 1.0, v76
	v_rcp_f32_e32 v126, v77
	v_rcp_f32_e32 v127, v120
	v_pk_add_f32 v[76:77], v[84:85], v[80:81] op_sel_hi:[1,0] neg_lo:[0,1] neg_hi:[0,1]
	v_pk_add_f32 v[84:85], v[98:99], v[80:81] op_sel_hi:[1,0] neg_lo:[0,1] neg_hi:[0,1]
	v_pk_mul_f32 v[98:99], v[88:89], v[88:89]
	v_pk_mul_f32 v[120:121], v[126:127], v[78:79]
	v_pk_mul_f32 v[78:79], v[72:73], v[72:73]
	v_pk_mul_f32 v[126:127], v[130:131], v[130:131]
	v_pk_mul_f32 v[132:133], v[96:97], v[96:97]
	v_pk_mul_f32 v[136:137], v[84:85], v[84:85]
	v_pk_mul_f32 v[138:139], v[128:129], v[128:129]
	v_pk_mul_f32 v[140:141], v[76:77], v[76:77]
	v_and_b32_e32 v143, 0xffff0000, v204
	v_lshlrev_b32_e32 v142, 16, v204
	v_and_b32_e32 v145, 0xffff0000, v208
	s_nop 0
	v_mul_f32_e32 v146, 0xbfb8aa3b, v145
	s_nop 0
	v_exp_f32_e32 v147, v146
	v_lshlrev_b32_e32 v144, 16, v208
	s_nop 0
	v_mul_f32_e32 v146, 0xbfb8aa3b, v144
	s_nop 0
	v_exp_f32_e32 v148, v146
	v_add_f32_e32 v146, 1.0, v147
	s_nop 0
	v_rcp_f32_e32 v151, v146
	v_add_f32_e32 v146, v98, v99
	s_nop 0
	v_add_f32_e32 v98, v78, v146
	v_add_f32_e32 v99, 1.0, v148
	v_add_f32_e32 v146, v79, v98
	v_rcp_f32_e32 v150, v99
	v_add_f32_e32 v78, v126, v146
	s_nop 0
	v_add_f32_e32 v79, v127, v78
	s_nop 0
	v_add_f32_e32 v78, v132, v79
	s_nop 0
	v_add_f32_e32 v79, v133, v78
	v_pk_mul_f32 v[98:99], v[150:151], v[144:145]
	v_pk_add_f32 v[126:127], v[100:101], v[80:81] op_sel_hi:[1,0] neg_lo:[0,1] neg_hi:[0,1]
	v_add_f32_e32 v78, v136, v79
	v_pk_mul_f32 v[80:81], v[126:127], v[126:127]
	v_add_f32_e32 v79, v137, v78
	s_nop 0
	v_add_f32_e32 v78, v80, v79
	s_nop 0
	v_add_f32_e32 v79, v81, v78
	s_nop 0
	v_add_f32_e32 v78, v138, v79
	s_nop 0
	v_add_f32_e32 v79, v139, v78
	s_nop 0
	v_add_f32_e32 v78, v140, v79
	s_nop 0
	v_add_f32_e32 v79, v141, v78
	ds_bpermute_b32 v78, v94, v79
	s_waitcnt lgkmcnt(0)
	v_add_f32_e32 v80, v79, v78
	ds_bpermute_b32 v78, v95, v80
	s_waitcnt lgkmcnt(0)
	v_add_f32_e32 v79, v80, v78
	s_nop 0
	v_fmamk_f32 v78, v79, 0x3c800000, v108
	s_nop 0
	v_cmp_gt_f32_e32 vcc, s11, v78
	v_mul_f32_e32 v79, 0x4b800000, v78
	s_nop 0
	v_cndmask_b32_e32 v80, v78, v79, vcc
	s_nop 0
	v_rsq_f32_e32 v78, v80
	s_nop 0
	v_mul_f32_e32 v79, 0x45800000, v78
	v_mov_b32_e32 v81, v205
	v_cndmask_b32_e32 v80, v78, v79, vcc
	s_nop 0
	v_pk_mul_f32 v[78:79], v[130:131], v[80:81] op_sel_hi:[1,0]
	v_pk_mul_f32 v[100:101], v[88:89], v[80:81] op_sel_hi:[1,0]
	v_pk_fma_f32 v[88:89], v[188:189], v[78:79], v[196:197]
	v_pk_mul_f32 v[78:79], v[96:97], v[80:81] op_sel_hi:[1,0]
	v_pk_fma_f32 v[96:97], v[192:193], v[100:101], v[200:201]
	v_pk_mul_f32 v[100:101], v[72:73], v[80:81] op_sel_hi:[1,0]
	v_pk_fma_f32 v[72:73], v[190:191], v[78:79], v[198:199]
	v_pk_fma_f32 v[78:79], v[194:195], v[100:101], v[202:203]
	v_pk_fma_f32 v[100:101], v[82:83], v[90:91], v[88:89] op_sel_hi:[0,1,1]
	v_pk_fma_f32 v[88:89], v[82:83], v[92:93], v[72:73] op_sel_hi:[0,1,1]
	v_pk_fma_f32 v[72:73], v[82:83], v[74:75], v[96:97] op_sel_hi:[0,1,1]
	v_pk_fma_f32 v[74:75], v[82:83], v[122:123], v[78:79] op_sel_hi:[0,1,1]
	v_pk_mul_f32 v[78:79], v[134:135], v[100:101]
	v_pk_mul_f32 v[90:91], v[120:121], v[88:89]
	v_pk_mul_f32 v[88:89], v[124:125], v[72:73]
	v_pk_mul_f32 v[72:73], v[102:103], v[74:75]
	v_cvt_pk_bf16_f32 v102, v78, v79
	v_cvt_pk_bf16_f32 v103, v90, v91
	v_cvt_pk_bf16_f32 v100, v88, v89
	v_cvt_pk_bf16_f32 v101, v72, v73
	global_store_dwordx4 v[86:87], v[100:103], off
	global_load_dwordx4 v[72:75], v[40:41], off offset:48
	global_load_dwordx4 v[88:91], v[40:41], off offset:32
	global_load_dwordx4 v[100:103], v[42:43], off offset:48
	global_load_dwordx4 v[120:123], v[42:43], off offset:32
	v_cmp_lt_i32_e32 vcc, s4, v71
	v_lshl_add_u64 v[44:45], v[44:45], 0, s[26:27]
	s_or_b64 s[38:39], vcc, s[38:39]
	s_waitcnt vmcnt(0)
	v_pk_mul_f32 v[78:79], v[84:85], v[80:81] op_sel_hi:[1,0]
	s_nop 0
	v_pk_fma_f32 v[84:85], v[88:89], v[78:79], v[120:121]
	s_nop 0
	v_pk_fma_f32 v[78:79], v[82:83], v[142:143], v[84:85] op_sel_hi:[0,1,1]
	s_nop 0
	v_pk_mul_f32 v[84:85], v[98:99], v[78:79]
	v_pk_mul_f32 v[78:79], v[126:127], v[80:81] op_sel_hi:[1,0]
	v_cvt_pk_bf16_f32 v96, v84, v85
	v_and_b32_e32 v85, 0xffff0000, v209
	v_lshlrev_b32_e32 v84, 16, v209
	s_nop 0
	v_mul_f32_e32 v97, 0xbfb8aa3b, v84
	v_pk_fma_f32 v[92:93], v[90:91], v[78:79], v[122:123]
	v_and_b32_e32 v79, 0xffff0000, v81
	v_lshlrev_b32_e32 v78, 16, v81
	v_mul_f32_e32 v88, 0xbfb8aa3b, v85
	v_exp_f32_e32 v89, v97
	v_exp_f32_e32 v90, v88
	v_pk_fma_f32 v[120:121], v[82:83], v[78:79], v[92:93] op_sel_hi:[0,1,1]
	v_add_f32_e32 v78, 1.0, v89
	v_add_f32_e32 v79, 1.0, v90
	v_rcp_f32_e32 v88, v78
	v_rcp_f32_e32 v89, v79
	s_nop 0
	v_pk_mul_f32 v[78:79], v[88:89], v[84:85]
	s_nop 0
	v_pk_mul_f32 v[84:85], v[78:79], v[120:121]
	v_mov_b32_e32 v88, v96
	v_cvt_pk_bf16_f32 v89, v84, v85
	v_lshlrev_b32_e32 v78, 16, v210
	s_nop 0
	v_mul_f32_e32 v84, 0xbfb8aa3b, v78
	s_nop 0
	v_exp_f32_e32 v85, v84
	v_and_b32_e32 v79, 0xffff0000, v210
	v_mov_b32_e32 v92, v80
	v_add_f32_e32 v93, 1.0, v85
	s_nop 0
	v_rcp_f32_e32 v80, v93
	v_pk_mul_f32 v[84:85], v[128:129], v[92:93] op_sel_hi:[1,0]
	v_mul_f32_e32 v96, 0xbfb8aa3b, v79
	s_nop 0
	v_exp_f32_e32 v97, v96
	v_pk_fma_f32 v[98:99], v[72:73], v[84:85], v[100:101]
	v_and_b32_e32 v85, 0xffff0000, v206
	v_lshlrev_b32_e32 v84, 16, v206
	v_add_f32_e32 v96, 1.0, v97
	s_nop 0
	v_rcp_f32_e32 v81, v96
	v_pk_fma_f32 v[96:97], v[82:83], v[84:85], v[98:99] op_sel_hi:[0,1,1]
	v_pk_mul_f32 v[84:85], v[80:81], v[78:79]
	s_nop 0
	v_pk_mul_f32 v[78:79], v[84:85], v[96:97]
	s_nop 0
	v_cvt_pk_bf16_f32 v90, v78, v79
	v_lshlrev_b32_e32 v78, 16, v211
	s_nop 0
	v_mul_f32_e32 v80, 0xbfb8aa3b, v78
	s_nop 0
	v_exp_f32_e32 v81, v80
	v_and_b32_e32 v79, 0xffff0000, v211
	v_mov_b32_e32 v84, v92
	v_add_f32_e32 v85, 1.0, v81
	s_nop 0
	v_rcp_f32_e32 v80, v85
	v_pk_mul_f32 v[92:93], v[76:77], v[84:85] op_sel_hi:[1,0]
	s_nop 0
	v_pk_fma_f32 v[76:77], v[92:93], v[74:75], v[102:103]
	v_and_b32_e32 v73, 0xffff0000, v207
	v_lshlrev_b32_e32 v72, 16, v207
	v_mul_f32_e32 v81, 0xbfb8aa3b, v79
	s_nop 0
	v_exp_f32_e32 v74, v81
	v_pk_fma_f32 v[84:85], v[82:83], v[72:73], v[76:77] op_sel_hi:[0,1,1]
	v_add_f32_e32 v72, 1.0, v74
	v_mov_b32_e32 v74, v80
	v_rcp_f32_e32 v75, v72
	s_nop 0
	v_pk_mul_f32 v[72:73], v[74:75], v[78:79]
	s_nop 0
	v_pk_mul_f32 v[74:75], v[72:73], v[84:85]
	s_nop 0
	v_cvt_pk_bf16_f32 v91, v74, v75
	global_store_dwordx4 v[86:87], v[88:91], off offset:16
	s_andn2_b64 exec, exec, s[38:39]
	s_cbranch_execnz .LBB0_829
